# early L1 invalidate overlapped with barrier arrive (late invalidate dropped when hand-off is XCD-local); redundant per-unit accumulator zeroing moved off the hot path
# speedup vs baseline: 1.0063x; 1.0063x over previous
; template <class Epi, class Sched, bool ALIGN_EPI = false, bool SP2 = false>
; __device__ __forceinline__ void gemm_phase(PG8_LAS unsigned char* lds, const Gemm g, const Sched& S, const Epi& E, const int tid_in) {
;     ...
; #pragma unroll
;         for (int a = 0; a < 2; ++a)
; #pragma unroll
;             for (int b = 0; b < 2; ++b)
; #pragma unroll
;                 for (int m = 0; m < 4; ++m)
; #pragma unroll
;                     for (int n = 0; n < 2; ++n) acc[a][b][m][n] = (f32x4){0.f, 0.f, 0.f, 0.f};
;         cur = nxt; cA = nA; cB = nB; ++ui;
.LBB0_118:
	s_andn2_b64 vcc, exec, s[18:19]
	s_cbranch_vccnz .Lzero_acc_1
	s_add_u32 s26, s26, 0x4000
	s_addc_u32 s27, s27, 0
	s_add_u32 s6, s28, 0x8000
	v_mov_b32_e32 v0, 0
	s_addc_u32 s7, s29, 0
	s_mov_b32 s28, 0
	v_mov_b32_e32 v1, v0
	v_mov_b32_e32 v2, v0
	v_mov_b32_e32 v3, v0
	v_mov_b32_e32 v4, v0
	v_mov_b32_e32 v5, v0
	v_mov_b32_e32 v6, v0
	v_mov_b32_e32 v7, v0
	v_mov_b32_e32 v16, v0
	v_mov_b32_e32 v17, v0
	v_mov_b32_e32 v18, v0
	v_mov_b32_e32 v19, v0
	v_mov_b32_e32 v20, v0
	v_mov_b32_e32 v21, v0
	v_mov_b32_e32 v22, v0
	v_mov_b32_e32 v23, v0
	v_mov_b32_e32 v32, v0
	v_mov_b32_e32 v33, v0
	v_mov_b32_e32 v34, v0
	v_mov_b32_e32 v35, v0
	v_mov_b32_e32 v36, v0
	v_mov_b32_e32 v37, v0
	v_mov_b32_e32 v38, v0
	v_mov_b32_e32 v39, v0
	v_mov_b32_e32 v48, v0
	v_mov_b32_e32 v49, v0
	v_mov_b32_e32 v50, v0
	v_mov_b32_e32 v51, v0
	v_mov_b32_e32 v52, v0
	v_mov_b32_e32 v53, v0
	v_mov_b32_e32 v54, v0
	v_mov_b32_e32 v55, v0
	v_mov_b32_e32 v8, v0
	v_mov_b32_e32 v9, v0
	v_mov_b32_e32 v10, v0
	v_mov_b32_e32 v11, v0
	v_mov_b32_e32 v12, v0
	v_mov_b32_e32 v13, v0
	v_mov_b32_e32 v14, v0
	v_mov_b32_e32 v15, v0
	v_mov_b32_e32 v24, v0
	v_mov_b32_e32 v25, v0
	v_mov_b32_e32 v26, v0
	v_mov_b32_e32 v27, v0
	v_mov_b32_e32 v28, v0
	v_mov_b32_e32 v29, v0
	v_mov_b32_e32 v30, v0
	v_mov_b32_e32 v31, v0
	v_mov_b32_e32 v40, v0
	v_mov_b32_e32 v41, v0
	v_mov_b32_e32 v42, v0
	v_mov_b32_e32 v43, v0
	v_mov_b32_e32 v44, v0
	v_mov_b32_e32 v45, v0
	v_mov_b32_e32 v46, v0
	v_mov_b32_e32 v47, v0
	v_mov_b32_e32 v56, v0
	v_mov_b32_e32 v57, v0
	v_mov_b32_e32 v58, v0
	v_mov_b32_e32 v59, v0
	v_mov_b32_e32 v60, v0
	v_mov_b32_e32 v61, v0
	v_mov_b32_e32 v62, v0
	v_mov_b32_e32 v63, v0
	v_mov_b32_e32 v64, v0
	v_mov_b32_e32 v65, v0
	v_mov_b32_e32 v66, v0
	v_mov_b32_e32 v67, v0
	v_mov_b32_e32 v68, v0
	v_mov_b32_e32 v69, v0
	v_mov_b32_e32 v70, v0
	v_mov_b32_e32 v71, v0
	v_mov_b32_e32 v80, v0
	v_mov_b32_e32 v81, v0
	v_mov_b32_e32 v82, v0
	v_mov_b32_e32 v83, v0
	v_mov_b32_e32 v84, v0
	v_mov_b32_e32 v85, v0
	v_mov_b32_e32 v86, v0
	v_mov_b32_e32 v87, v0
	v_mov_b32_e32 v96, v0
	v_mov_b32_e32 v97, v0
	v_mov_b32_e32 v98, v0
	v_mov_b32_e32 v99, v0
	v_mov_b32_e32 v100, v0
	v_mov_b32_e32 v101, v0
	v_mov_b32_e32 v102, v0
	v_mov_b32_e32 v103, v0
	v_mov_b32_e32 v112, v0
	v_mov_b32_e32 v113, v0
	v_mov_b32_e32 v114, v0
	v_mov_b32_e32 v115, v0
	v_mov_b32_e32 v116, v0
	v_mov_b32_e32 v117, v0
	v_mov_b32_e32 v118, v0
	v_mov_b32_e32 v119, v0
	v_mov_b32_e32 v72, v0
	v_mov_b32_e32 v73, v0
	v_mov_b32_e32 v74, v0
	v_mov_b32_e32 v75, v0
	v_mov_b32_e32 v76, v0
	v_mov_b32_e32 v77, v0
	v_mov_b32_e32 v78, v0
	v_mov_b32_e32 v79, v0
	v_mov_b32_e32 v88, v0
	v_mov_b32_e32 v89, v0
	v_mov_b32_e32 v90, v0
	v_mov_b32_e32 v91, v0
	v_mov_b32_e32 v92, v0
	v_mov_b32_e32 v93, v0
	v_mov_b32_e32 v94, v0
	v_mov_b32_e32 v95, v0
	v_mov_b32_e32 v104, v0
	v_mov_b32_e32 v105, v0
	v_mov_b32_e32 v106, v0
	v_mov_b32_e32 v107, v0
	v_mov_b32_e32 v108, v0
	v_mov_b32_e32 v109, v0
	v_mov_b32_e32 v110, v0
	v_mov_b32_e32 v111, v0
	v_mov_b32_e32 v124, v0
	v_mov_b32_e32 v125, v0
	v_mov_b32_e32 v126, v0
	v_mov_b32_e32 v127, v0
	v_mov_b32_e32 v120, v0
	v_mov_b32_e32 v121, v0
	v_mov_b32_e32 v122, v0
	v_mov_b32_e32 v123, v0

; template <class Epi, class Sched, bool ALIGN_EPI = false, bool SP2 = false>
; __device__ __forceinline__ void gemm_phase(PG8_LAS unsigned char* lds, const Gemm g, const Sched& S, const Epi& E, const int tid_in) {
;     ...
; #pragma unroll
;         for (int a = 0; a < 2; ++a)
; #pragma unroll
;             for (int b = 0; b < 2; ++b)
; #pragma unroll
;                 for (int m = 0; m < 4; ++m)
; #pragma unroll
;                     for (int n = 0; n < 2; ++n) acc[a][b][m][n] = (f32x4){0.f, 0.f, 0.f, 0.f};
;         cur = nxt; cA = nA; cB = nB; ++ui;
.LBB0_143:
	s_andn2_b64 vcc, exec, s[18:19]
	s_cbranch_vccnz .Lzero_acc_2
	s_add_u32 s26, s26, 0x4000
	s_addc_u32 s27, s27, 0
	s_add_u32 s6, s28, 0x8000
	v_mov_b32_e32 v0, 0
	s_addc_u32 s7, s29, 0
	s_mov_b32 s28, 0
	v_mov_b32_e32 v1, v0
	v_mov_b32_e32 v2, v0
	v_mov_b32_e32 v3, v0
	v_mov_b32_e32 v4, v0
	v_mov_b32_e32 v5, v0
	v_mov_b32_e32 v6, v0
	v_mov_b32_e32 v7, v0
	v_mov_b32_e32 v16, v0
	v_mov_b32_e32 v17, v0
	v_mov_b32_e32 v18, v0
	v_mov_b32_e32 v19, v0
	v_mov_b32_e32 v20, v0
	v_mov_b32_e32 v21, v0
	v_mov_b32_e32 v22, v0
	v_mov_b32_e32 v23, v0
	v_mov_b32_e32 v32, v0
	v_mov_b32_e32 v33, v0
	v_mov_b32_e32 v34, v0
	v_mov_b32_e32 v35, v0
	v_mov_b32_e32 v36, v0
	v_mov_b32_e32 v37, v0
	v_mov_b32_e32 v38, v0
	v_mov_b32_e32 v39, v0
	v_mov_b32_e32 v48, v0
	v_mov_b32_e32 v49, v0
	v_mov_b32_e32 v50, v0
	v_mov_b32_e32 v51, v0
	v_mov_b32_e32 v52, v0
	v_mov_b32_e32 v53, v0
	v_mov_b32_e32 v54, v0
	v_mov_b32_e32 v55, v0
	v_mov_b32_e32 v8, v0
	v_mov_b32_e32 v9, v0
	v_mov_b32_e32 v10, v0
	v_mov_b32_e32 v11, v0
	v_mov_b32_e32 v12, v0
	v_mov_b32_e32 v13, v0
	v_mov_b32_e32 v14, v0
	v_mov_b32_e32 v15, v0
	v_mov_b32_e32 v24, v0
	v_mov_b32_e32 v25, v0
	v_mov_b32_e32 v26, v0
	v_mov_b32_e32 v27, v0
	v_mov_b32_e32 v28, v0
	v_mov_b32_e32 v29, v0
	v_mov_b32_e32 v30, v0
	v_mov_b32_e32 v31, v0
	v_mov_b32_e32 v40, v0
	v_mov_b32_e32 v41, v0
	v_mov_b32_e32 v42, v0
	v_mov_b32_e32 v43, v0
	v_mov_b32_e32 v44, v0
	v_mov_b32_e32 v45, v0
	v_mov_b32_e32 v46, v0
	v_mov_b32_e32 v47, v0
	v_mov_b32_e32 v56, v0
	v_mov_b32_e32 v57, v0
	v_mov_b32_e32 v58, v0
	v_mov_b32_e32 v59, v0
	v_mov_b32_e32 v60, v0
	v_mov_b32_e32 v61, v0
	v_mov_b32_e32 v62, v0
	v_mov_b32_e32 v63, v0
	v_mov_b32_e32 v64, v0
	v_mov_b32_e32 v65, v0
	v_mov_b32_e32 v66, v0
	v_mov_b32_e32 v67, v0
	v_mov_b32_e32 v68, v0
	v_mov_b32_e32 v69, v0
	v_mov_b32_e32 v70, v0
	v_mov_b32_e32 v71, v0
	v_mov_b32_e32 v80, v0
	v_mov_b32_e32 v81, v0
	v_mov_b32_e32 v82, v0
	v_mov_b32_e32 v83, v0
	v_mov_b32_e32 v84, v0
	v_mov_b32_e32 v85, v0
	v_mov_b32_e32 v86, v0
	v_mov_b32_e32 v87, v0
	v_mov_b32_e32 v96, v0
	v_mov_b32_e32 v97, v0
	v_mov_b32_e32 v98, v0
	v_mov_b32_e32 v99, v0
	v_mov_b32_e32 v100, v0
	v_mov_b32_e32 v101, v0
	v_mov_b32_e32 v102, v0
	v_mov_b32_e32 v103, v0
	v_mov_b32_e32 v112, v0
	v_mov_b32_e32 v113, v0
	v_mov_b32_e32 v114, v0
	v_mov_b32_e32 v115, v0
	v_mov_b32_e32 v116, v0
	v_mov_b32_e32 v117, v0
	v_mov_b32_e32 v118, v0
	v_mov_b32_e32 v119, v0
	v_mov_b32_e32 v72, v0
	v_mov_b32_e32 v73, v0
	v_mov_b32_e32 v74, v0
	v_mov_b32_e32 v75, v0
	v_mov_b32_e32 v76, v0
	v_mov_b32_e32 v77, v0
	v_mov_b32_e32 v78, v0
	v_mov_b32_e32 v79, v0
	v_mov_b32_e32 v88, v0
	v_mov_b32_e32 v89, v0
	v_mov_b32_e32 v90, v0
	v_mov_b32_e32 v91, v0
	v_mov_b32_e32 v92, v0
	v_mov_b32_e32 v93, v0
	v_mov_b32_e32 v94, v0
	v_mov_b32_e32 v95, v0
	v_mov_b32_e32 v104, v0
	v_mov_b32_e32 v105, v0
	v_mov_b32_e32 v106, v0
	v_mov_b32_e32 v107, v0
	v_mov_b32_e32 v108, v0
	v_mov_b32_e32 v109, v0
	v_mov_b32_e32 v110, v0
	v_mov_b32_e32 v111, v0
	v_mov_b32_e32 v120, v0
	v_mov_b32_e32 v121, v0
	v_mov_b32_e32 v122, v0
	v_mov_b32_e32 v123, v0
	v_mov_b32_e32 v124, v0
	v_mov_b32_e32 v125, v0
	v_mov_b32_e32 v126, v0
	v_mov_b32_e32 v127, v0

; template <class Epi, class Sched, bool ALIGN_EPI = false, bool SP2 = false>
; __device__ __forceinline__ void gemm_phase(PG8_LAS unsigned char* lds, const Gemm g, const Sched& S, const Epi& E, const int tid_in) {
;     ...
; #pragma unroll
;         for (int a = 0; a < 2; ++a)
; #pragma unroll
;             for (int b = 0; b < 2; ++b)
; #pragma unroll
;                 for (int m = 0; m < 4; ++m)
; #pragma unroll
;                     for (int n = 0; n < 2; ++n) acc[a][b][m][n] = (f32x4){0.f, 0.f, 0.f, 0.f};
;         cur = nxt; cA = nA; cB = nB; ++ui;
.LBB0_232:
	s_andn2_b64 vcc, exec, s[26:27]
	s_cbranch_vccnz .Lzero_acc_3
	s_add_u32 s78, s46, s18
	s_addc_u32 s96, s47, s19
	s_add_u32 s97, s48, 0x8000
	v_mov_b32_e32 v0, 0
	s_addc_u32 s6, s49, 0
	s_mov_b64 s[42:43], 0
	v_mov_b32_e32 v1, v0
	v_mov_b32_e32 v2, v0
	v_mov_b32_e32 v3, v0
	v_mov_b32_e32 v4, v0
	v_mov_b32_e32 v5, v0
	v_mov_b32_e32 v6, v0
	v_mov_b32_e32 v7, v0
	v_mov_b32_e32 v16, v0
	v_mov_b32_e32 v17, v0
	v_mov_b32_e32 v18, v0
	v_mov_b32_e32 v19, v0
	v_mov_b32_e32 v20, v0
	v_mov_b32_e32 v21, v0
	v_mov_b32_e32 v22, v0
	v_mov_b32_e32 v23, v0
	v_mov_b32_e32 v32, v0
	v_mov_b32_e32 v33, v0
	v_mov_b32_e32 v34, v0
	v_mov_b32_e32 v35, v0
	v_mov_b32_e32 v36, v0
	v_mov_b32_e32 v37, v0
	v_mov_b32_e32 v38, v0
	v_mov_b32_e32 v39, v0
	v_mov_b32_e32 v48, v0
	v_mov_b32_e32 v49, v0
	v_mov_b32_e32 v50, v0
	v_mov_b32_e32 v51, v0
	v_mov_b32_e32 v52, v0
	v_mov_b32_e32 v53, v0
	v_mov_b32_e32 v54, v0
	v_mov_b32_e32 v55, v0
	v_mov_b32_e32 v8, v0
	v_mov_b32_e32 v9, v0
	v_mov_b32_e32 v10, v0
	v_mov_b32_e32 v11, v0
	v_mov_b32_e32 v12, v0
	v_mov_b32_e32 v13, v0
	v_mov_b32_e32 v14, v0
	v_mov_b32_e32 v15, v0
	v_mov_b32_e32 v24, v0
	v_mov_b32_e32 v25, v0
	v_mov_b32_e32 v26, v0
	v_mov_b32_e32 v27, v0
	v_mov_b32_e32 v28, v0
	v_mov_b32_e32 v29, v0
	v_mov_b32_e32 v30, v0
	v_mov_b32_e32 v31, v0
	v_mov_b32_e32 v40, v0
	v_mov_b32_e32 v41, v0
	v_mov_b32_e32 v42, v0
	v_mov_b32_e32 v43, v0
	v_mov_b32_e32 v44, v0
	v_mov_b32_e32 v45, v0
	v_mov_b32_e32 v46, v0
	v_mov_b32_e32 v47, v0
	v_mov_b32_e32 v56, v0
	v_mov_b32_e32 v57, v0
	v_mov_b32_e32 v58, v0
	v_mov_b32_e32 v59, v0
	v_mov_b32_e32 v60, v0
	v_mov_b32_e32 v61, v0
	v_mov_b32_e32 v62, v0
	v_mov_b32_e32 v63, v0
	v_mov_b32_e32 v68, v0
	v_mov_b32_e32 v69, v0
	v_mov_b32_e32 v70, v0
	v_mov_b32_e32 v71, v0
	v_mov_b32_e32 v72, v0
	v_mov_b32_e32 v73, v0
	v_mov_b32_e32 v74, v0
	v_mov_b32_e32 v75, v0
	v_mov_b32_e32 v92, v0
	v_mov_b32_e32 v93, v0
	v_mov_b32_e32 v94, v0
	v_mov_b32_e32 v95, v0
	v_mov_b32_e32 v96, v0
	v_mov_b32_e32 v97, v0
	v_mov_b32_e32 v98, v0
	v_mov_b32_e32 v99, v0
	v_mov_b32_e32 v112, v0
	v_mov_b32_e32 v113, v0
	v_mov_b32_e32 v114, v0
	v_mov_b32_e32 v115, v0
	v_mov_b32_e32 v116, v0
	v_mov_b32_e32 v117, v0
	v_mov_b32_e32 v118, v0
	v_mov_b32_e32 v119, v0
	v_mov_b32_e32 v128, v0
	v_mov_b32_e32 v129, v0
	v_mov_b32_e32 v130, v0
	v_mov_b32_e32 v131, v0
	v_mov_b32_e32 v132, v0
	v_mov_b32_e32 v133, v0
	v_mov_b32_e32 v134, v0
	v_mov_b32_e32 v135, v0
	v_mov_b32_e32 v80, v0
	v_mov_b32_e32 v81, v0
	v_mov_b32_e32 v82, v0
	v_mov_b32_e32 v83, v0
	v_mov_b32_e32 v84, v0
	v_mov_b32_e32 v85, v0
	v_mov_b32_e32 v86, v0
	v_mov_b32_e32 v87, v0
	v_mov_b32_e32 v100, v0
	v_mov_b32_e32 v101, v0
	v_mov_b32_e32 v102, v0
	v_mov_b32_e32 v103, v0
	v_mov_b32_e32 v104, v0
	v_mov_b32_e32 v105, v0
	v_mov_b32_e32 v106, v0
	v_mov_b32_e32 v107, v0
	v_mov_b32_e32 v120, v0
	v_mov_b32_e32 v121, v0
	v_mov_b32_e32 v122, v0
	v_mov_b32_e32 v123, v0
	v_mov_b32_e32 v124, v0
	v_mov_b32_e32 v125, v0
	v_mov_b32_e32 v126, v0
	v_mov_b32_e32 v127, v0
	v_mov_b32_e32 v136, v0
	v_mov_b32_e32 v137, v0
	v_mov_b32_e32 v138, v0
	v_mov_b32_e32 v139, v0
	v_mov_b32_e32 v140, v0
	v_mov_b32_e32 v141, v0
	v_mov_b32_e32 v142, v0
	v_mov_b32_e32 v143, v0

; __device__ __forceinline__ unsigned xb_add(unsigned* p, unsigned v) { return __hip_atomic_fetch_add(p, v, __ATOMIC_RELAXED, __HIP_MEMORY_SCOPE_AGENT); }
; __device__ __forceinline__ void xcd_barrier(const XcdBarrier& b) {
;     asm volatile("s_waitcnt vmcnt(0)" ::: "memory");
;     __syncthreads();
;     if (threadIdx.x == 0) {
;         unsigned* bar = b.bar;
;         __builtin_amdgcn_s_waitcnt(0);
;         unsigned nloc = b.st[0], nx = b.st[1];
;         if (nloc == 0u) { xcd_barrier_complete(bar, b.x, nloc, nx); b.st[0] = nloc; b.st[1] = nx; }
;         const unsigned old = xb_add(&bar[XB_XSUB(b.x)], 1u);
;         const unsigned gen = old / nloc;
;         if (old + 1u == (gen + 1u) * nloc) {
; __global__ void __launch_bounds__(NWAVES * 64, 2) fwd_megakernel(Args args) {
;     ...
;         if (d.kind != K_FINAL) xcd_barrier(bar);
.LBB0_475:
	s_load_dword s0, s[14:15], 0x70
	v_readlane_b32 s20, v254, 62
	v_readlane_b32 s21, v254, 63
	s_waitcnt lgkmcnt(0)
	s_cmp_eq_u32 s0, 7
	s_cbranch_scc1 .LBB0_64
	s_waitcnt vmcnt(0)
	s_waitcnt vmcnt(0)
	s_barrier
	s_and_saveexec_b64 s[4:5], s[82:83]
	s_cbranch_execz .LBB0_63
	s_and_b32 s0, s88, 0xff
	s_mul_i32 s0, s0, 27
	s_lshr_b32 s0, s0, 9
	s_mul_i32 s0, s0, 19
	s_sub_i32 s0, s88, s0
	s_lshr_b32 s0, 0x9048, s0
	s_andn2_b32 s0, 1, s0
	v_readlane_b32 s1, v255, 20
	s_cmp_lg_u32 s1, 0
	s_cselect_b32 s0, s0, 0
	v_writelane_b32 v255, s0, 26
	v_readlane_b32 s0, v254, 53
	s_waitcnt vmcnt(0) expcnt(0) lgkmcnt(0)
	s_nop 0
	v_mov_b32_e32 v0, s0
	ds_read_b32 v2, v0
	v_readlane_b32 s0, v254, 54
	s_waitcnt lgkmcnt(0)
	v_cmp_ne_u32_e32 vcc, 0, v2
	v_mov_b32_e32 v0, s0
	ds_read_b32 v0, v0
	s_cbranch_vccnz .LBB0_492
	s_mov_b32 s0, 1
	s_branch .LBB0_480

; __device__ __forceinline__ unsigned xb_ld(unsigned* p)              { return __hip_atomic_load(p, __ATOMIC_RELAXED, __HIP_MEMORY_SCOPE_AGENT); }
; __device__ __forceinline__ unsigned xb_add(unsigned* p, unsigned v) { return __hip_atomic_fetch_add(p, v, __ATOMIC_RELAXED, __HIP_MEMORY_SCOPE_AGENT); }
; #define XB_SPIN(cond, bar) do { unsigned _sp = 0; while (cond) { __builtin_amdgcn_s_sleep(1); \
;     if ((++_sp & 255u) == 0u) { if (xb_ld(&(bar)[XB_TMO])) break; if (_sp > XB_SPIN_CAP) { atomicAdd(&(bar)[XB_TMO], 1u); break; } } } } while (0)
; __device__ __forceinline__ void xcd_barrier(const XcdBarrier& b) {
;     ...
;         const unsigned old = xb_add(&bar[XB_XSUB(b.x)], 1u);
;         const unsigned gen = old / nloc;
;         if (old + 1u == (gen + 1u) * nloc) {
;             __builtin_amdgcn_fence(__ATOMIC_RELEASE, "agent");
;             asm volatile("s_waitcnt vmcnt(0)" ::: "memory");
;             const unsigned og = xb_add(&bar[XB_TOP], 1u);
;             const unsigned tg = og / nx;
;             if (og + 1u == (tg + 1u) * nx) xb_add(&bar[XB_TOPGEN], 1u);
;             else XB_SPIN(xb_ld(&bar[XB_TOPGEN]) == tg, bar);
;             __builtin_amdgcn_fence(__ATOMIC_ACQUIRE, "agent");
;             xb_add(&bar[XB_XGEN(b.x)], 1u);
;             asm volatile("s_waitcnt vmcnt(0)" ::: "memory");
;         } else {
;             XB_SPIN(xb_ld(&bar[XB_XGEN(b.x)]) == gen, bar);
.LBB0_492:
	s_mov_b64 s[8:9], exec
	v_mbcnt_lo_u32_b32 v1, s8, 0
	v_mbcnt_hi_u32_b32 v1, s9, v1
	v_cmp_eq_u32_e32 vcc, 0, v1
	s_and_saveexec_b64 s[6:7], vcc
	s_cbranch_execz .LBB0_494
	s_bcnt1_i32_b64 s0, s[8:9]
	v_mov_b32_e32 v3, s0
	v_readlane_b32 s0, v254, 45
	v_readlane_b32 s1, v254, 46
	s_nop 4
	global_atomic_add v3, v209, v3, s[0:1] sc0
	buffer_inv sc1
.LBB0_494:
	s_or_b64 exec, exec, s[6:7]
	v_cvt_f32_u32_e32 v4, v2
	s_waitcnt vmcnt(1)
	v_readfirstlane_b32 s0, v3
	v_sub_u32_e32 v3, 0, v2
	v_rcp_iflag_f32_e32 v4, v4
	v_add_u32_e32 v5, s0, v1
	v_mul_f32_e32 v4, 0x4f7ffffe, v4
	v_cvt_u32_f32_e32 v4, v4
	v_mul_lo_u32 v1, v3, v4
	v_mul_hi_u32 v1, v4, v1
	v_add_u32_e32 v1, v4, v1
	v_mul_hi_u32 v1, v5, v1
	v_mul_lo_u32 v3, v1, v2
	v_sub_u32_e32 v3, v5, v3
	v_add_u32_e32 v4, 1, v1
	v_cmp_ge_u32_e32 vcc, v3, v2
	s_nop 1
	v_cndmask_b32_e32 v1, v1, v4, vcc
	v_sub_u32_e32 v4, v3, v2
	v_cndmask_b32_e32 v3, v3, v4, vcc
	v_add_u32_e32 v4, 1, v1
	v_cmp_ge_u32_e32 vcc, v3, v2
	v_add_u32_e32 v3, 1, v5
	s_nop 0
	v_cndmask_b32_e32 v1, v1, v4, vcc
	v_mul_lo_u32 v4, v2, v1
	v_add_u32_e32 v2, v4, v2
	v_cmp_ne_u32_e32 vcc, v3, v2
	s_and_saveexec_b64 s[0:1], vcc
	s_xor_b64 s[6:7], exec, s[0:1]
	s_cbranch_execz .LBB0_508
	v_readlane_b32 s0, v254, 47
	v_readlane_b32 s1, v254, 48
	s_waitcnt lgkmcnt(0)
	s_nop 3
	global_load_dword v0, v209, s[0:1] sc1
	s_waitcnt vmcnt(0)
	v_cmp_eq_u32_e32 vcc, v0, v1
	s_and_saveexec_b64 s[8:9], vcc
	s_cbranch_execz .LBB0_507
	s_mov_b32 s0, 1
	s_mov_b64 s[10:11], 0
	s_branch .LBB0_498

; __device__ __forceinline__ unsigned xb_ld(unsigned* p)              { return __hip_atomic_load(p, __ATOMIC_RELAXED, __HIP_MEMORY_SCOPE_AGENT); }
; #define XB_SPIN(cond, bar) do { unsigned _sp = 0; while (cond) { __builtin_amdgcn_s_sleep(1); \
;     if ((++_sp & 255u) == 0u) { if (xb_ld(&(bar)[XB_TMO])) break; if (_sp > XB_SPIN_CAP) { atomicAdd(&(bar)[XB_TMO], 1u); break; } } } } while (0)
; __device__ __forceinline__ void xcd_barrier(const XcdBarrier& b) {
;     ...
;         } else {
;             XB_SPIN(xb_ld(&bar[XB_XGEN(b.x)]) == gen, bar);
;             __builtin_amdgcn_fence(__ATOMIC_ACQUIRE, "agent");
;             asm volatile("s_waitcnt vmcnt(0)" ::: "memory");
;         }
.LBB0_507:
	s_or_b64 exec, exec, s[8:9]
	s_waitcnt vmcnt(0)
	v_readlane_b32 s0, v255, 20
	s_cmp_lg_u32 s0, 0
	s_cbranch_scc1 .Lxb_inv_done
	buffer_inv sc1

; __device__ __forceinline__ unsigned xb_add(unsigned* p, unsigned v) { return __hip_atomic_fetch_add(p, v, __ATOMIC_RELAXED, __HIP_MEMORY_SCOPE_AGENT); }
; __device__ __forceinline__ void xcd_barrier(const XcdBarrier& b) {
;     ...
;         if (old + 1u == (gen + 1u) * nloc) {
;             __builtin_amdgcn_fence(__ATOMIC_RELEASE, "agent");
;             asm volatile("s_waitcnt vmcnt(0)" ::: "memory");
;             const unsigned og = xb_add(&bar[XB_TOP], 1u);
;             const unsigned tg = og / nx;
;             if (og + 1u == (tg + 1u) * nx) xb_add(&bar[XB_TOPGEN], 1u);
.LBB0_508:
	s_andn2_saveexec_b64 s[0:1], s[6:7]
	s_cbranch_execz .LBB0_63
	v_readlane_b32 s2, v255, 26
	s_waitcnt lgkmcnt(0)
	s_cmp_lg_u32 s2, 0
	s_cbranch_scc1 .Lxb_local_release
	s_mov_b64 s[6:7], exec
	buffer_wbl2 sc1
	s_waitcnt lgkmcnt(0)
	s_waitcnt vmcnt(0)
	v_mbcnt_lo_u32_b32 v1, s6, 0
	v_mbcnt_hi_u32_b32 v1, s7, v1
	v_cmp_eq_u32_e32 vcc, 0, v1
	s_and_saveexec_b64 s[8:9], vcc
	s_cbranch_execz .LBB0_511
	s_bcnt1_i32_b64 s0, s[6:7]
	v_mov_b32_e32 v2, s0
	v_readlane_b32 s0, v254, 49
	v_readlane_b32 s1, v254, 50
	s_nop 4
	global_atomic_add v2, v209, v2, s[0:1] sc0

; __device__ __forceinline__ unsigned xb_ld(unsigned* p)              { return __hip_atomic_load(p, __ATOMIC_RELAXED, __HIP_MEMORY_SCOPE_AGENT); }
; __device__ __forceinline__ unsigned xb_add(unsigned* p, unsigned v) { return __hip_atomic_fetch_add(p, v, __ATOMIC_RELAXED, __HIP_MEMORY_SCOPE_AGENT); }
; #define XB_SPIN(cond, bar) do { unsigned _sp = 0; while (cond) { __builtin_amdgcn_s_sleep(1); \
;     if ((++_sp & 255u) == 0u) { if (xb_ld(&(bar)[XB_TMO])) break; if (_sp > XB_SPIN_CAP) { atomicAdd(&(bar)[XB_TMO], 1u); break; } } } } while (0)
; template <class Epi, class Sched, bool ALIGN_EPI = false, bool SP2 = false>
; __device__ __forceinline__ void gemm_phase(PG8_LAS unsigned char* lds, const Gemm g, const Sched& S, const Epi& E, const int tid_in) {
;     ...
; #pragma unroll
;         for (int a = 0; a < 2; ++a)
; #pragma unroll
;             for (int b = 0; b < 2; ++b)
; #pragma unroll
;                 for (int m = 0; m < 4; ++m)
; #pragma unroll
;                     for (int n = 0; n < 2; ++n) acc[a][b][m][n] = (f32x4){0.f, 0.f, 0.f, 0.f};
; __device__ __forceinline__ void xcd_barrier(const XcdBarrier& b) {
;     ...
;             const unsigned og = xb_add(&bar[XB_TOP], 1u);
;             const unsigned tg = og / nx;
;             if (og + 1u == (tg + 1u) * nx) xb_add(&bar[XB_TOPGEN], 1u);
;             else XB_SPIN(xb_ld(&bar[XB_TOPGEN]) == tg, bar);
;             __builtin_amdgcn_fence(__ATOMIC_ACQUIRE, "agent");
;             xb_add(&bar[XB_XGEN(b.x)], 1u);
;             asm volatile("s_waitcnt vmcnt(0)" ::: "memory");
.LBB0_525:
	s_or_b64 exec, exec, s[6:7]
	s_mov_b64 s[6:7], exec
	v_mbcnt_lo_u32_b32 v0, s6, 0
	v_mbcnt_hi_u32_b32 v0, s7, v0
	v_cmp_eq_u32_e32 vcc, 0, v0
	s_waitcnt vmcnt(0)
	v_readlane_b32 s0, v255, 20
	s_cmp_lg_u32 s0, 0
	s_cbranch_scc1 .Lxb_inv_done2
	buffer_inv sc1
.Lxb_inv_done2:
	s_and_saveexec_b64 s[8:9], vcc
	s_cbranch_execz .LBB0_62
	s_bcnt1_i32_b64 s0, s[6:7]
	v_mov_b32_e32 v0, s0
	v_readlane_b32 s0, v254, 47
	v_readlane_b32 s1, v254, 48
	s_nop 4
	global_atomic_add v209, v0, s[0:1]
	s_branch .LBB0_62
.Lzero_acc_1:
	v_mov_b32_e32 v123, 0
	v_mov_b32_e32 v122, v123
	v_mov_b32_e32 v121, v123
	v_mov_b32_e32 v120, v123
	v_mov_b32_e32 v127, v123
	v_mov_b32_e32 v126, v123
	v_mov_b32_e32 v125, v123
	v_mov_b32_e32 v124, v123
	v_mov_b32_e32 v111, v123
	v_mov_b32_e32 v110, v123
	v_mov_b32_e32 v109, v123
	v_mov_b32_e32 v108, v123
	v_mov_b32_e32 v107, v123
	v_mov_b32_e32 v106, v123
	v_mov_b32_e32 v105, v123
	v_mov_b32_e32 v104, v123
	v_mov_b32_e32 v95, v123
	v_mov_b32_e32 v94, v123
	v_mov_b32_e32 v93, v123
	v_mov_b32_e32 v92, v123
	v_mov_b32_e32 v91, v123
	v_mov_b32_e32 v90, v123
	v_mov_b32_e32 v89, v123
	v_mov_b32_e32 v88, v123
	v_mov_b32_e32 v79, v123
	v_mov_b32_e32 v78, v123
	v_mov_b32_e32 v77, v123
	v_mov_b32_e32 v76, v123
	v_mov_b32_e32 v75, v123
	v_mov_b32_e32 v74, v123
	v_mov_b32_e32 v73, v123
	v_mov_b32_e32 v72, v123
	v_mov_b32_e32 v119, v123
	v_mov_b32_e32 v118, v123
	v_mov_b32_e32 v117, v123
	v_mov_b32_e32 v116, v123
	v_mov_b32_e32 v115, v123
	v_mov_b32_e32 v114, v123
	v_mov_b32_e32 v113, v123
	v_mov_b32_e32 v112, v123
	v_mov_b32_e32 v103, v123
	v_mov_b32_e32 v102, v123
	v_mov_b32_e32 v101, v123
	v_mov_b32_e32 v100, v123
	v_mov_b32_e32 v99, v123
	v_mov_b32_e32 v98, v123
	v_mov_b32_e32 v97, v123
	v_mov_b32_e32 v96, v123
	v_mov_b32_e32 v87, v123
	v_mov_b32_e32 v86, v123
	v_mov_b32_e32 v85, v123
	v_mov_b32_e32 v84, v123
	v_mov_b32_e32 v83, v123
	v_mov_b32_e32 v82, v123
	v_mov_b32_e32 v81, v123
	v_mov_b32_e32 v80, v123
	v_mov_b32_e32 v71, v123
	v_mov_b32_e32 v70, v123
	v_mov_b32_e32 v69, v123
	v_mov_b32_e32 v68, v123
	v_mov_b32_e32 v67, v123
	v_mov_b32_e32 v66, v123
	v_mov_b32_e32 v65, v123
	v_mov_b32_e32 v64, v123
	v_mov_b32_e32 v63, v123
	v_mov_b32_e32 v62, v123
	v_mov_b32_e32 v61, v123
	v_mov_b32_e32 v60, v123
	v_mov_b32_e32 v59, v123
	v_mov_b32_e32 v58, v123
	v_mov_b32_e32 v57, v123
	v_mov_b32_e32 v56, v123
	v_mov_b32_e32 v47, v123
	v_mov_b32_e32 v46, v123
	v_mov_b32_e32 v45, v123
	v_mov_b32_e32 v44, v123
	v_mov_b32_e32 v43, v123
	v_mov_b32_e32 v42, v123
	v_mov_b32_e32 v41, v123
	v_mov_b32_e32 v40, v123
	v_mov_b32_e32 v31, v123
	v_mov_b32_e32 v30, v123
	v_mov_b32_e32 v29, v123
	v_mov_b32_e32 v28, v123
	v_mov_b32_e32 v27, v123
	v_mov_b32_e32 v26, v123
	v_mov_b32_e32 v25, v123
	v_mov_b32_e32 v24, v123
	v_mov_b32_e32 v15, v123
	v_mov_b32_e32 v14, v123
	v_mov_b32_e32 v13, v123
	v_mov_b32_e32 v12, v123
	v_mov_b32_e32 v11, v123
	v_mov_b32_e32 v10, v123
	v_mov_b32_e32 v9, v123
	v_mov_b32_e32 v8, v123
	v_mov_b32_e32 v55, v123
	v_mov_b32_e32 v54, v123
	v_mov_b32_e32 v53, v123
	v_mov_b32_e32 v52, v123
	v_mov_b32_e32 v51, v123
	v_mov_b32_e32 v50, v123
	v_mov_b32_e32 v49, v123
	v_mov_b32_e32 v48, v123
	v_mov_b32_e32 v39, v123
	v_mov_b32_e32 v38, v123
	v_mov_b32_e32 v37, v123
	v_mov_b32_e32 v36, v123
	v_mov_b32_e32 v35, v123
	v_mov_b32_e32 v34, v123
	v_mov_b32_e32 v33, v123
	v_mov_b32_e32 v32, v123
	v_mov_b32_e32 v23, v123
	v_mov_b32_e32 v22, v123
	v_mov_b32_e32 v21, v123
	v_mov_b32_e32 v20, v123
	v_mov_b32_e32 v19, v123
	v_mov_b32_e32 v18, v123
	v_mov_b32_e32 v17, v123
	v_mov_b32_e32 v16, v123
	v_mov_b32_e32 v7, v123
	v_mov_b32_e32 v6, v123
	v_mov_b32_e32 v5, v123
	v_mov_b32_e32 v4, v123
	v_mov_b32_e32 v3, v123
	v_mov_b32_e32 v2, v123
	v_mov_b32_e32 v1, v123
	v_mov_b32_e32 v0, v123
	s_branch .LBB0_121
; __device__ __forceinline__ unsigned xb_add(unsigned* p, unsigned v) { return __hip_atomic_fetch_add(p, v, __ATOMIC_RELAXED, __HIP_MEMORY_SCOPE_AGENT); }
; template <class Epi, class Sched, bool ALIGN_EPI = false, bool SP2 = false>
; __device__ __forceinline__ void gemm_phase(PG8_LAS unsigned char* lds, const Gemm g, const Sched& S, const Epi& E, const int tid_in) {
;     ...
; #pragma unroll
;         for (int a = 0; a < 2; ++a)
; #pragma unroll
;             for (int b = 0; b < 2; ++b)
; #pragma unroll
;                 for (int m = 0; m < 4; ++m)
; #pragma unroll
;                     for (int n = 0; n < 2; ++n) acc[a][b][m][n] = (f32x4){0.f, 0.f, 0.f, 0.f};
; __device__ __forceinline__ void xcd_barrier(const XcdBarrier& b) {
;     ...
;             __builtin_amdgcn_fence(__ATOMIC_ACQUIRE, "agent");
;             xb_add(&bar[XB_XGEN(b.x)], 1u);
;             asm volatile("s_waitcnt vmcnt(0)" ::: "memory");
.Lzero_acc_2:
	v_mov_b32_e32 v127, 0
	v_mov_b32_e32 v126, v127
	v_mov_b32_e32 v125, v127
	v_mov_b32_e32 v124, v127
	v_mov_b32_e32 v123, v127
	v_mov_b32_e32 v122, v127
	v_mov_b32_e32 v121, v127
	v_mov_b32_e32 v120, v127
	v_mov_b32_e32 v111, v127
	v_mov_b32_e32 v110, v127
	v_mov_b32_e32 v109, v127
	v_mov_b32_e32 v108, v127
	v_mov_b32_e32 v107, v127
	v_mov_b32_e32 v106, v127
	v_mov_b32_e32 v105, v127
	v_mov_b32_e32 v104, v127
	v_mov_b32_e32 v95, v127
	v_mov_b32_e32 v94, v127
	v_mov_b32_e32 v93, v127
	v_mov_b32_e32 v92, v127
	v_mov_b32_e32 v91, v127
	v_mov_b32_e32 v90, v127
	v_mov_b32_e32 v89, v127
	v_mov_b32_e32 v88, v127
	v_mov_b32_e32 v79, v127
	v_mov_b32_e32 v78, v127
	v_mov_b32_e32 v77, v127
	v_mov_b32_e32 v76, v127
	v_mov_b32_e32 v75, v127
	v_mov_b32_e32 v74, v127
	v_mov_b32_e32 v73, v127
	v_mov_b32_e32 v72, v127
	v_mov_b32_e32 v119, v127
	v_mov_b32_e32 v118, v127
	v_mov_b32_e32 v117, v127
	v_mov_b32_e32 v116, v127
	v_mov_b32_e32 v115, v127
	v_mov_b32_e32 v114, v127
	v_mov_b32_e32 v113, v127
	v_mov_b32_e32 v112, v127
	v_mov_b32_e32 v103, v127
	v_mov_b32_e32 v102, v127
	v_mov_b32_e32 v101, v127
	v_mov_b32_e32 v100, v127
	v_mov_b32_e32 v99, v127
	v_mov_b32_e32 v98, v127
	v_mov_b32_e32 v97, v127
	v_mov_b32_e32 v96, v127
	v_mov_b32_e32 v87, v127
	v_mov_b32_e32 v86, v127
	v_mov_b32_e32 v85, v127
	v_mov_b32_e32 v84, v127
	v_mov_b32_e32 v83, v127
	v_mov_b32_e32 v82, v127
	v_mov_b32_e32 v81, v127
	v_mov_b32_e32 v80, v127
	v_mov_b32_e32 v71, v127
	v_mov_b32_e32 v70, v127
	v_mov_b32_e32 v69, v127
	v_mov_b32_e32 v68, v127
	v_mov_b32_e32 v67, v127
	v_mov_b32_e32 v66, v127
	v_mov_b32_e32 v65, v127
	v_mov_b32_e32 v64, v127
	v_mov_b32_e32 v63, v127
	v_mov_b32_e32 v62, v127
	v_mov_b32_e32 v61, v127
	v_mov_b32_e32 v60, v127
	v_mov_b32_e32 v59, v127
	v_mov_b32_e32 v58, v127
	v_mov_b32_e32 v57, v127
	v_mov_b32_e32 v56, v127
	v_mov_b32_e32 v47, v127
	v_mov_b32_e32 v46, v127
	v_mov_b32_e32 v45, v127
	v_mov_b32_e32 v44, v127
	v_mov_b32_e32 v43, v127
	v_mov_b32_e32 v42, v127
	v_mov_b32_e32 v41, v127
	v_mov_b32_e32 v40, v127
	v_mov_b32_e32 v31, v127
	v_mov_b32_e32 v30, v127
	v_mov_b32_e32 v29, v127
	v_mov_b32_e32 v28, v127
	v_mov_b32_e32 v27, v127
	v_mov_b32_e32 v26, v127
	v_mov_b32_e32 v25, v127
	v_mov_b32_e32 v24, v127
	v_mov_b32_e32 v15, v127
	v_mov_b32_e32 v14, v127
	v_mov_b32_e32 v13, v127
	v_mov_b32_e32 v12, v127
	v_mov_b32_e32 v11, v127
	v_mov_b32_e32 v10, v127
	v_mov_b32_e32 v9, v127
	v_mov_b32_e32 v8, v127
	v_mov_b32_e32 v55, v127
	v_mov_b32_e32 v54, v127
	v_mov_b32_e32 v53, v127
	v_mov_b32_e32 v52, v127
	v_mov_b32_e32 v51, v127
	v_mov_b32_e32 v50, v127
	v_mov_b32_e32 v49, v127
	v_mov_b32_e32 v48, v127
	v_mov_b32_e32 v39, v127
	v_mov_b32_e32 v38, v127
	v_mov_b32_e32 v37, v127
	v_mov_b32_e32 v36, v127
	v_mov_b32_e32 v35, v127
	v_mov_b32_e32 v34, v127
	v_mov_b32_e32 v33, v127
	v_mov_b32_e32 v32, v127
	v_mov_b32_e32 v23, v127
	v_mov_b32_e32 v22, v127
	v_mov_b32_e32 v21, v127
	v_mov_b32_e32 v20, v127
	v_mov_b32_e32 v19, v127
	v_mov_b32_e32 v18, v127
	v_mov_b32_e32 v17, v127
	v_mov_b32_e32 v16, v127
	v_mov_b32_e32 v7, v127
	v_mov_b32_e32 v6, v127
	v_mov_b32_e32 v5, v127
	v_mov_b32_e32 v4, v127
	v_mov_b32_e32 v3, v127
	v_mov_b32_e32 v2, v127
	v_mov_b32_e32 v1, v127
	v_mov_b32_e32 v0, v127
	s_branch .LBB0_146
.Lzero_acc_3:
	v_mov_b32_e32 v143, 0
	v_mov_b32_e32 v142, v143
	v_mov_b32_e32 v141, v143
	v_mov_b32_e32 v140, v143
	v_mov_b32_e32 v139, v143
	v_mov_b32_e32 v138, v143
	v_mov_b32_e32 v137, v143
	v_mov_b32_e32 v136, v143
	v_mov_b32_e32 v127, v143
	v_mov_b32_e32 v126, v143
	v_mov_b32_e32 v125, v143
	v_mov_b32_e32 v124, v143
	v_mov_b32_e32 v123, v143
	v_mov_b32_e32 v122, v143
	v_mov_b32_e32 v121, v143
	v_mov_b32_e32 v120, v143
	v_mov_b32_e32 v107, v143
	v_mov_b32_e32 v106, v143
	v_mov_b32_e32 v105, v143
	v_mov_b32_e32 v104, v143
	v_mov_b32_e32 v103, v143
	v_mov_b32_e32 v102, v143
	v_mov_b32_e32 v101, v143
	v_mov_b32_e32 v100, v143
	v_mov_b32_e32 v87, v143
	v_mov_b32_e32 v86, v143
	v_mov_b32_e32 v85, v143
	v_mov_b32_e32 v84, v143
	v_mov_b32_e32 v83, v143
	v_mov_b32_e32 v82, v143
	v_mov_b32_e32 v81, v143
	v_mov_b32_e32 v80, v143
	v_mov_b32_e32 v135, v143
	v_mov_b32_e32 v134, v143
	v_mov_b32_e32 v133, v143
	v_mov_b32_e32 v132, v143
	v_mov_b32_e32 v131, v143
	v_mov_b32_e32 v130, v143
	v_mov_b32_e32 v129, v143
	v_mov_b32_e32 v128, v143
	v_mov_b32_e32 v119, v143
	v_mov_b32_e32 v118, v143
	v_mov_b32_e32 v117, v143
	v_mov_b32_e32 v116, v143
	v_mov_b32_e32 v115, v143
	v_mov_b32_e32 v114, v143
	v_mov_b32_e32 v113, v143
	v_mov_b32_e32 v112, v143
	v_mov_b32_e32 v99, v143
	v_mov_b32_e32 v98, v143
	v_mov_b32_e32 v97, v143
	v_mov_b32_e32 v96, v143
	v_mov_b32_e32 v95, v143
	v_mov_b32_e32 v94, v143
	v_mov_b32_e32 v93, v143
	v_mov_b32_e32 v92, v143
	v_mov_b32_e32 v75, v143
	v_mov_b32_e32 v74, v143
	v_mov_b32_e32 v73, v143
	v_mov_b32_e32 v72, v143
	v_mov_b32_e32 v71, v143
	v_mov_b32_e32 v70, v143
	v_mov_b32_e32 v69, v143
	v_mov_b32_e32 v68, v143
	v_mov_b32_e32 v63, v143
	v_mov_b32_e32 v62, v143
	v_mov_b32_e32 v61, v143
	v_mov_b32_e32 v60, v143
	v_mov_b32_e32 v59, v143
	v_mov_b32_e32 v58, v143
	v_mov_b32_e32 v57, v143
	v_mov_b32_e32 v56, v143
	v_mov_b32_e32 v47, v143
	v_mov_b32_e32 v46, v143
	v_mov_b32_e32 v45, v143
	v_mov_b32_e32 v44, v143
	v_mov_b32_e32 v43, v143
	v_mov_b32_e32 v42, v143
	v_mov_b32_e32 v41, v143
	v_mov_b32_e32 v40, v143
	v_mov_b32_e32 v31, v143
	v_mov_b32_e32 v30, v143
	v_mov_b32_e32 v29, v143
	v_mov_b32_e32 v28, v143
	v_mov_b32_e32 v27, v143
	v_mov_b32_e32 v26, v143
	v_mov_b32_e32 v25, v143
	v_mov_b32_e32 v24, v143
	v_mov_b32_e32 v15, v143
	v_mov_b32_e32 v14, v143
	v_mov_b32_e32 v13, v143
	v_mov_b32_e32 v12, v143
	v_mov_b32_e32 v11, v143
	v_mov_b32_e32 v10, v143
	v_mov_b32_e32 v9, v143
	v_mov_b32_e32 v8, v143
	v_mov_b32_e32 v55, v143
	v_mov_b32_e32 v54, v143
	v_mov_b32_e32 v53, v143
	v_mov_b32_e32 v52, v143
	v_mov_b32_e32 v51, v143
	v_mov_b32_e32 v50, v143
	v_mov_b32_e32 v49, v143
	v_mov_b32_e32 v48, v143
	v_mov_b32_e32 v39, v143
	v_mov_b32_e32 v38, v143
	v_mov_b32_e32 v37, v143
	v_mov_b32_e32 v36, v143
	v_mov_b32_e32 v35, v143
	v_mov_b32_e32 v34, v143
	v_mov_b32_e32 v33, v143
	v_mov_b32_e32 v32, v143
	v_mov_b32_e32 v23, v143
	v_mov_b32_e32 v22, v143
	v_mov_b32_e32 v21, v143
	v_mov_b32_e32 v20, v143
	v_mov_b32_e32 v19, v143
	v_mov_b32_e32 v18, v143
	v_mov_b32_e32 v17, v143
	v_mov_b32_e32 v16, v143
	v_mov_b32_e32 v7, v143
	v_mov_b32_e32 v6, v143
	v_mov_b32_e32 v5, v143
	v_mov_b32_e32 v4, v143
	v_mov_b32_e32 v3, v143
	v_mov_b32_e32 v2, v143
	v_mov_b32_e32 v1, v143
	v_mov_b32_e32 v0, v143
	s_branch .LBB0_235
.Lxb_local_release:
	s_mov_b64 s[6:7], exec
	v_mbcnt_lo_u32_b32 v0, s6, 0
	v_mbcnt_hi_u32_b32 v0, s7, v0
	v_cmp_eq_u32_e32 vcc, 0, v0
	s_waitcnt vmcnt(0)
	s_and_saveexec_b64 s[8:9], vcc
	s_cbranch_execz .LBB0_62
	s_bcnt1_i32_b64 s0, s[6:7]
	v_mov_b32_e32 v0, s0
	v_readlane_b32 s0, v254, 47
	v_readlane_b32 s1, v254, 48
	s_nop 4
	global_atomic_add v209, v0, s[0:1]
	s_branch .LBB0_62
